# adaLN: k rows interleaved over the 8 waves (wave w rows w,w+8,..) with permuted sv table, so a CU streams 8 consecutive rows
# baseline (speedup 1.0000x reference)
; DI void phase_prologue(const Frame& F0, const Args& a) {
;     ...
;         for (int i = F.tid; i < 3 * DM; i += 512) { const int mb = i / DM, k = i % DM; const float cv = mb < 2 ? a.c[mb * DM + k] : a.c_ctx[k]; sv[i] = cv / (1.0f + __expf(-cv)); }
.LBB0_14:
	s_or_b64 exec, exec, s[6:7]
	global_load_dword v2, v[2:3], off
	s_movk_i32 s6, 0x15ff
	v_add_u32_e32 v6, 0x200, v5
	v_cmp_lt_i32_e32 vcc, s6, v5
	s_or_b64 s[4:5], vcc, s[4:5]
	s_waitcnt vmcnt(0)
	v_mul_f32_e32 v3, 0xbfb8aa3b, v2
	v_exp_f32_e32 v3, v3
	s_nop 0
	v_add_f32_e32 v3, 1.0, v3
	v_div_scale_f32 v5, s[6:7], v3, v3, v2
	v_rcp_f32_e32 v7, v5
	v_div_scale_f32 v8, vcc, v2, v3, v2
	v_fma_f32 v9, -v5, v7, 1.0
	v_fmac_f32_e32 v7, v9, v7
	v_mul_f32_e32 v9, v8, v7
	v_fma_f32 v10, -v5, v9, v8
	v_fmac_f32_e32 v9, v10, v7
	v_fma_f32 v5, -v5, v9, v8
	v_div_fmas_f32 v5, v5, v7, v9
	v_div_fixup_f32 v2, v5, v3, v2
	v_add_u32_e32 v7, 0xfffffe00, v6
	v_and_b32_e32 v8, 7, v7
	v_lshlrev_b32_e32 v8, 10, v8
	v_bfe_u32 v9, v7, 3, 8
	v_lshl_add_u32 v8, v9, 2, v8
	v_lshrrev_b32_e32 v9, 11, v7
	v_lshl_add_u32 v8, v9, 13, v8
	ds_write_b32 v8, v2
	v_add_u32_e32 v4, 0x800, v4
	v_mov_b32_e32 v5, v6
	s_andn2_b64 exec, exec, s[4:5]
	s_cbranch_execz .LBB0_19

; #define GAS __attribute__((address_space(1)))
; #define LAS __attribute__((address_space(3)))
; DI void phase_prologue(const Frame& F0, const Args& a) {
;     ...
;             if (F.lane < 48) {
;                 const int kb = F.wave * 256;
; #pragma unroll 16
;                 for (int k = 0; k < 256; ++k) {
;                     const f32x4 w = __builtin_nontemporal_load((const GAS f32x4*)(W + (size_t)(kb + k) * NADA + F.lane * 4));
;                     const float s0 = sv[kb + k], s1 = sv[DM + kb + k], s2 = sv[2 * DM + kb + k];
;                     acc0 += w * s0; acc1 += w * s1; acc2 += w * s2;
;                 }
;                 *(LAS f32x4*)(red + (F.wave * 3 + 0) * 192 + F.lane * 4) = acc0;
;                 *(LAS f32x4*)(red + (F.wave * 3 + 1) * 192 + F.lane * 4) = acc1;
;                 *(LAS f32x4*)(red + (F.wave * 3 + 2) * 192 + F.lane * 4) = acc2;
.LBB0_24:
	v_readfirstlane_b32 s92, v58
	v_readfirstlane_b32 s93, v59
	s_mul_i32 s95, s44, 0xbf4000
	s_sub_u32 s92, s92, s95
	s_subb_u32 s93, s93, 0
	v_lshlrev_b32_e32 v95, 4, v78
	s_mul_i32 s94, s44, 0x3000
	s_add_i32 s94, s94, 0xa800
	v_add_u32_e32 v94, s94, v95
	s_nop 3
	s_mov_b32 m0, s94
	s_nop 0
	global_load_lds_dwordx4 v95, s[92:93] nt
	s_add_u32 s92, s92, 0x60000
	s_addc_u32 s93, s93, 0
	s_add_u32 m0, s94, 0x300
	s_nop 0
	global_load_lds_dwordx4 v95, s[92:93] nt
	s_add_u32 s92, s92, 0x60000
	s_addc_u32 s93, s93, 0
	s_add_u32 m0, s94, 0x600
	s_nop 0
	global_load_lds_dwordx4 v95, s[92:93] nt
	s_add_u32 s92, s92, 0x60000
	s_addc_u32 s93, s93, 0
	s_add_u32 m0, s94, 0x900
	s_nop 0
	global_load_lds_dwordx4 v95, s[92:93] nt
	s_add_u32 s92, s92, 0x60000
	s_addc_u32 s93, s93, 0
	s_add_u32 m0, s94, 0xc00
	s_nop 0
	global_load_lds_dwordx4 v95, s[92:93] nt
	s_add_u32 s92, s92, 0x60000
	s_addc_u32 s93, s93, 0
	s_add_u32 m0, s94, 0xf00
	s_nop 0
	global_load_lds_dwordx4 v95, s[92:93] nt
	s_add_u32 s92, s92, 0x60000
	s_addc_u32 s93, s93, 0
	s_add_u32 m0, s94, 0x1200
	s_nop 0
	global_load_lds_dwordx4 v95, s[92:93] nt
	s_add_u32 s92, s92, 0x60000
	s_addc_u32 s93, s93, 0
	s_add_u32 m0, s94, 0x1500
	s_nop 0
	global_load_lds_dwordx4 v95, s[92:93] nt
	s_add_u32 s92, s92, 0x60000
	s_addc_u32 s93, s93, 0
	s_add_u32 m0, s94, 0x1800
	s_nop 0
	global_load_lds_dwordx4 v95, s[92:93] nt
	s_add_u32 s92, s92, 0x60000
	s_addc_u32 s93, s93, 0
	s_add_u32 m0, s94, 0x1b00
	s_nop 0
	global_load_lds_dwordx4 v95, s[92:93] nt
	s_add_u32 s92, s92, 0x60000
	s_addc_u32 s93, s93, 0
	s_add_u32 m0, s94, 0x1e00
	s_nop 0
	global_load_lds_dwordx4 v95, s[92:93] nt
	s_add_u32 s92, s92, 0x60000
	s_addc_u32 s93, s93, 0
	s_add_u32 m0, s94, 0x2100
	s_nop 0
	global_load_lds_dwordx4 v95, s[92:93] nt
	s_add_u32 s92, s92, 0x60000
	s_addc_u32 s93, s93, 0
	s_add_u32 m0, s94, 0x2400
	s_nop 0
	global_load_lds_dwordx4 v95, s[92:93] nt
	s_add_u32 s92, s92, 0x60000
	s_addc_u32 s93, s93, 0
	s_add_u32 m0, s94, 0x2700
	s_nop 0
	global_load_lds_dwordx4 v95, s[92:93] nt
	s_add_u32 s92, s92, 0x60000
	s_addc_u32 s93, s93, 0
	s_add_u32 m0, s94, 0x2a00
	s_nop 0
	global_load_lds_dwordx4 v95, s[92:93] nt
	s_add_u32 s92, s92, 0x60000
	s_addc_u32 s93, s93, 0
	s_add_u32 m0, s94, 0x2d00
	s_nop 0
	global_load_lds_dwordx4 v95, s[92:93] nt
	s_add_u32 s92, s92, 0x60000
	s_addc_u32 s93, s93, 0
	s_movk_i32 s95, 15
.Lada_loop:
	v_mov_b32_e32 v93, s12
	ds_read_b128 v[160:163], v93
	ds_read_b128 v[164:167], v93 offset:16
	ds_read_b128 v[168:171], v93 offset:32
	ds_read_b128 v[172:175], v93 offset:48
	ds_read_b128 v[176:179], v93 offset:8192
	ds_read_b128 v[180:183], v93 offset:8208
	ds_read_b128 v[184:187], v93 offset:8224
	ds_read_b128 v[188:191], v93 offset:8240
	ds_read_b128 v[192:195], v93 offset:16384
	ds_read_b128 v[196:199], v93 offset:16400
	ds_read_b128 v[200:203], v93 offset:16416
	ds_read_b128 v[204:207], v93 offset:16432
	s_add_i32 s12, s12, 64
	s_waitcnt vmcnt(12)
	ds_read_b128 v[96:99], v94
	ds_read_b128 v[100:103], v94 offset:768
	ds_read_b128 v[104:107], v94 offset:1536
	ds_read_b128 v[108:111], v94 offset:2304
	s_waitcnt lgkmcnt(0)
	v_pk_fma_f32 v[6:7], v[96:97], v[160:161], v[6:7] op_sel_hi:[1,0,1]
	v_pk_fma_f32 v[8:9], v[98:99], v[160:161], v[8:9] op_sel_hi:[1,0,1]
	v_pk_fma_f32 v[10:11], v[96:97], v[176:177], v[10:11] op_sel_hi:[1,0,1]
	v_pk_fma_f32 v[12:13], v[98:99], v[176:177], v[12:13] op_sel_hi:[1,0,1]
	v_pk_fma_f32 v[14:15], v[96:97], v[192:193], v[14:15] op_sel_hi:[1,0,1]
	v_pk_fma_f32 v[16:17], v[98:99], v[192:193], v[16:17] op_sel_hi:[1,0,1]
	v_pk_fma_f32 v[6:7], v[100:101], v[160:161], v[6:7] op_sel:[0,1,0]
	v_pk_fma_f32 v[8:9], v[102:103], v[160:161], v[8:9] op_sel:[0,1,0]
	v_pk_fma_f32 v[10:11], v[100:101], v[176:177], v[10:11] op_sel:[0,1,0]
	v_pk_fma_f32 v[12:13], v[102:103], v[176:177], v[12:13] op_sel:[0,1,0]
	v_pk_fma_f32 v[14:15], v[100:101], v[192:193], v[14:15] op_sel:[0,1,0]
	v_pk_fma_f32 v[16:17], v[102:103], v[192:193], v[16:17] op_sel:[0,1,0]
	v_pk_fma_f32 v[6:7], v[104:105], v[162:163], v[6:7] op_sel_hi:[1,0,1]
	v_pk_fma_f32 v[8:9], v[106:107], v[162:163], v[8:9] op_sel_hi:[1,0,1]
	v_pk_fma_f32 v[10:11], v[104:105], v[178:179], v[10:11] op_sel_hi:[1,0,1]
	v_pk_fma_f32 v[12:13], v[106:107], v[178:179], v[12:13] op_sel_hi:[1,0,1]
	v_pk_fma_f32 v[14:15], v[104:105], v[194:195], v[14:15] op_sel_hi:[1,0,1]
	v_pk_fma_f32 v[16:17], v[106:107], v[194:195], v[16:17] op_sel_hi:[1,0,1]
	v_pk_fma_f32 v[6:7], v[108:109], v[162:163], v[6:7] op_sel:[0,1,0]
	v_pk_fma_f32 v[8:9], v[110:111], v[162:163], v[8:9] op_sel:[0,1,0]
	v_pk_fma_f32 v[10:11], v[108:109], v[178:179], v[10:11] op_sel:[0,1,0]
	v_pk_fma_f32 v[12:13], v[110:111], v[178:179], v[12:13] op_sel:[0,1,0]
	v_pk_fma_f32 v[14:15], v[108:109], v[194:195], v[14:15] op_sel:[0,1,0]
	v_pk_fma_f32 v[16:17], v[110:111], v[194:195], v[16:17] op_sel:[0,1,0]
	s_mov_b32 m0, s94
	s_nop 0
	global_load_lds_dwordx4 v95, s[92:93] nt
	s_add_u32 s92, s92, 0x60000
	s_addc_u32 s93, s93, 0
	s_add_u32 m0, s94, 0x300
	s_nop 0
	global_load_lds_dwordx4 v95, s[92:93] nt
	s_add_u32 s92, s92, 0x60000
	s_addc_u32 s93, s93, 0
	s_add_u32 m0, s94, 0x600
	s_nop 0
	global_load_lds_dwordx4 v95, s[92:93] nt
	s_add_u32 s92, s92, 0x60000
	s_addc_u32 s93, s93, 0
	s_add_u32 m0, s94, 0x900
	s_nop 0
	global_load_lds_dwordx4 v95, s[92:93] nt
	s_add_u32 s92, s92, 0x60000
	s_addc_u32 s93, s93, 0
	s_waitcnt vmcnt(12)
	ds_read_b128 v[112:115], v94 offset:3072
	ds_read_b128 v[116:119], v94 offset:3840
	ds_read_b128 v[120:123], v94 offset:4608
	ds_read_b128 v[124:127], v94 offset:5376
	s_waitcnt lgkmcnt(0)
; #define GAS __attribute__((address_space(1)))
; #define LAS __attribute__((address_space(3)))
; DI void phase_prologue(const Frame& F0, const Args& a) {
;     ...
;             if (F.lane < 48) {
;                 const int kb = F.wave * 256;
; #pragma unroll 16
;                 for (int k = 0; k < 256; ++k) {
;                     const f32x4 w = __builtin_nontemporal_load((const GAS f32x4*)(W + (size_t)(kb + k) * NADA + F.lane * 4));
;                     const float s0 = sv[kb + k], s1 = sv[DM + kb + k], s2 = sv[2 * DM + kb + k];
;                     acc0 += w * s0; acc1 += w * s1; acc2 += w * s2;
;                 }
;                 *(LAS f32x4*)(red + (F.wave * 3 + 0) * 192 + F.lane * 4) = acc0;
;                 *(LAS f32x4*)(red + (F.wave * 3 + 1) * 192 + F.lane * 4) = acc1;
;                 *(LAS f32x4*)(red + (F.wave * 3 + 2) * 192 + F.lane * 4) = acc2;
	v_pk_fma_f32 v[6:7], v[112:113], v[164:165], v[6:7] op_sel_hi:[1,0,1]
	v_pk_fma_f32 v[8:9], v[114:115], v[164:165], v[8:9] op_sel_hi:[1,0,1]
	v_pk_fma_f32 v[10:11], v[112:113], v[180:181], v[10:11] op_sel_hi:[1,0,1]
	v_pk_fma_f32 v[12:13], v[114:115], v[180:181], v[12:13] op_sel_hi:[1,0,1]
	v_pk_fma_f32 v[14:15], v[112:113], v[196:197], v[14:15] op_sel_hi:[1,0,1]
	v_pk_fma_f32 v[16:17], v[114:115], v[196:197], v[16:17] op_sel_hi:[1,0,1]
	v_pk_fma_f32 v[6:7], v[116:117], v[164:165], v[6:7] op_sel:[0,1,0]
	v_pk_fma_f32 v[8:9], v[118:119], v[164:165], v[8:9] op_sel:[0,1,0]
	v_pk_fma_f32 v[10:11], v[116:117], v[180:181], v[10:11] op_sel:[0,1,0]
	v_pk_fma_f32 v[12:13], v[118:119], v[180:181], v[12:13] op_sel:[0,1,0]
	v_pk_fma_f32 v[14:15], v[116:117], v[196:197], v[14:15] op_sel:[0,1,0]
	v_pk_fma_f32 v[16:17], v[118:119], v[196:197], v[16:17] op_sel:[0,1,0]
	v_pk_fma_f32 v[6:7], v[120:121], v[166:167], v[6:7] op_sel_hi:[1,0,1]
	v_pk_fma_f32 v[8:9], v[122:123], v[166:167], v[8:9] op_sel_hi:[1,0,1]
	v_pk_fma_f32 v[10:11], v[120:121], v[182:183], v[10:11] op_sel_hi:[1,0,1]
	v_pk_fma_f32 v[12:13], v[122:123], v[182:183], v[12:13] op_sel_hi:[1,0,1]
	v_pk_fma_f32 v[14:15], v[120:121], v[198:199], v[14:15] op_sel_hi:[1,0,1]
	v_pk_fma_f32 v[16:17], v[122:123], v[198:199], v[16:17] op_sel_hi:[1,0,1]
	v_pk_fma_f32 v[6:7], v[124:125], v[166:167], v[6:7] op_sel:[0,1,0]
	v_pk_fma_f32 v[8:9], v[126:127], v[166:167], v[8:9] op_sel:[0,1,0]
	v_pk_fma_f32 v[10:11], v[124:125], v[182:183], v[10:11] op_sel:[0,1,0]
	v_pk_fma_f32 v[12:13], v[126:127], v[182:183], v[12:13] op_sel:[0,1,0]
	v_pk_fma_f32 v[14:15], v[124:125], v[198:199], v[14:15] op_sel:[0,1,0]
	v_pk_fma_f32 v[16:17], v[126:127], v[198:199], v[16:17] op_sel:[0,1,0]
	s_add_u32 m0, s94, 0xc00
	s_nop 0
	global_load_lds_dwordx4 v95, s[92:93] nt
	s_add_u32 s92, s92, 0x60000
	s_addc_u32 s93, s93, 0
	s_add_u32 m0, s94, 0xf00
	s_nop 0
	global_load_lds_dwordx4 v95, s[92:93] nt
	s_add_u32 s92, s92, 0x60000
	s_addc_u32 s93, s93, 0
	s_add_u32 m0, s94, 0x1200
	s_nop 0
	global_load_lds_dwordx4 v95, s[92:93] nt
	s_add_u32 s92, s92, 0x60000
	s_addc_u32 s93, s93, 0
	s_add_u32 m0, s94, 0x1500
	s_nop 0
	global_load_lds_dwordx4 v95, s[92:93] nt
	s_add_u32 s92, s92, 0x60000
	s_addc_u32 s93, s93, 0
	s_waitcnt vmcnt(12)
	ds_read_b128 v[128:131], v94 offset:6144
	ds_read_b128 v[132:135], v94 offset:6912
	ds_read_b128 v[136:139], v94 offset:7680
	ds_read_b128 v[140:143], v94 offset:8448
	s_waitcnt lgkmcnt(0)
	v_pk_fma_f32 v[6:7], v[128:129], v[168:169], v[6:7] op_sel_hi:[1,0,1]
	v_pk_fma_f32 v[8:9], v[130:131], v[168:169], v[8:9] op_sel_hi:[1,0,1]
	v_pk_fma_f32 v[10:11], v[128:129], v[184:185], v[10:11] op_sel_hi:[1,0,1]
	v_pk_fma_f32 v[12:13], v[130:131], v[184:185], v[12:13] op_sel_hi:[1,0,1]
	v_pk_fma_f32 v[14:15], v[128:129], v[200:201], v[14:15] op_sel_hi:[1,0,1]
	v_pk_fma_f32 v[16:17], v[130:131], v[200:201], v[16:17] op_sel_hi:[1,0,1]
	v_pk_fma_f32 v[6:7], v[132:133], v[168:169], v[6:7] op_sel:[0,1,0]
	v_pk_fma_f32 v[8:9], v[134:135], v[168:169], v[8:9] op_sel:[0,1,0]
	v_pk_fma_f32 v[10:11], v[132:133], v[184:185], v[10:11] op_sel:[0,1,0]
	v_pk_fma_f32 v[12:13], v[134:135], v[184:185], v[12:13] op_sel:[0,1,0]
	v_pk_fma_f32 v[14:15], v[132:133], v[200:201], v[14:15] op_sel:[0,1,0]
	v_pk_fma_f32 v[16:17], v[134:135], v[200:201], v[16:17] op_sel:[0,1,0]
	v_pk_fma_f32 v[6:7], v[136:137], v[170:171], v[6:7] op_sel_hi:[1,0,1]
	v_pk_fma_f32 v[8:9], v[138:139], v[170:171], v[8:9] op_sel_hi:[1,0,1]
	v_pk_fma_f32 v[10:11], v[136:137], v[186:187], v[10:11] op_sel_hi:[1,0,1]
	v_pk_fma_f32 v[12:13], v[138:139], v[186:187], v[12:13] op_sel_hi:[1,0,1]
	v_pk_fma_f32 v[14:15], v[136:137], v[202:203], v[14:15] op_sel_hi:[1,0,1]
	v_pk_fma_f32 v[16:17], v[138:139], v[202:203], v[16:17] op_sel_hi:[1,0,1]
	v_pk_fma_f32 v[6:7], v[140:141], v[170:171], v[6:7] op_sel:[0,1,0]
	v_pk_fma_f32 v[8:9], v[142:143], v[170:171], v[8:9] op_sel:[0,1,0]
	v_pk_fma_f32 v[10:11], v[140:141], v[186:187], v[10:11] op_sel:[0,1,0]
	v_pk_fma_f32 v[12:13], v[142:143], v[186:187], v[12:13] op_sel:[0,1,0]
	v_pk_fma_f32 v[14:15], v[140:141], v[202:203], v[14:15] op_sel:[0,1,0]
	v_pk_fma_f32 v[16:17], v[142:143], v[202:203], v[16:17] op_sel:[0,1,0]
	s_add_u32 m0, s94, 0x1800
	s_nop 0
	global_load_lds_dwordx4 v95, s[92:93] nt
	s_add_u32 s92, s92, 0x60000
	s_addc_u32 s93, s93, 0
	s_add_u32 m0, s94, 0x1b00
	s_nop 0
	global_load_lds_dwordx4 v95, s[92:93] nt
	s_add_u32 s92, s92, 0x60000
	s_addc_u32 s93, s93, 0
	s_add_u32 m0, s94, 0x1e00
	s_nop 0
	global_load_lds_dwordx4 v95, s[92:93] nt
	s_add_u32 s92, s92, 0x60000
	s_addc_u32 s93, s93, 0
	s_add_u32 m0, s94, 0x2100
	s_nop 0
	global_load_lds_dwordx4 v95, s[92:93] nt
	s_add_u32 s92, s92, 0x60000
	s_addc_u32 s93, s93, 0
	s_waitcnt vmcnt(12)
	ds_read_b128 v[144:147], v94 offset:9216
	ds_read_b128 v[148:151], v94 offset:9984
	ds_read_b128 v[152:155], v94 offset:10752
	ds_read_b128 v[156:159], v94 offset:11520
	s_waitcnt lgkmcnt(0)
; #define GAS __attribute__((address_space(1)))
; #define LAS __attribute__((address_space(3)))
; DI void phase_prologue(const Frame& F0, const Args& a) {
;     ...
;             if (F.lane < 48) {
;                 const int kb = F.wave * 256;
; #pragma unroll 16
;                 for (int k = 0; k < 256; ++k) {
;                     const f32x4 w = __builtin_nontemporal_load((const GAS f32x4*)(W + (size_t)(kb + k) * NADA + F.lane * 4));
;                     const float s0 = sv[kb + k], s1 = sv[DM + kb + k], s2 = sv[2 * DM + kb + k];
;                     acc0 += w * s0; acc1 += w * s1; acc2 += w * s2;
;                 }
;                 *(LAS f32x4*)(red + (F.wave * 3 + 0) * 192 + F.lane * 4) = acc0;
;                 *(LAS f32x4*)(red + (F.wave * 3 + 1) * 192 + F.lane * 4) = acc1;
;                 *(LAS f32x4*)(red + (F.wave * 3 + 2) * 192 + F.lane * 4) = acc2;
	v_pk_fma_f32 v[6:7], v[144:145], v[172:173], v[6:7] op_sel_hi:[1,0,1]
	v_pk_fma_f32 v[8:9], v[146:147], v[172:173], v[8:9] op_sel_hi:[1,0,1]
	v_pk_fma_f32 v[10:11], v[144:145], v[188:189], v[10:11] op_sel_hi:[1,0,1]
	v_pk_fma_f32 v[12:13], v[146:147], v[188:189], v[12:13] op_sel_hi:[1,0,1]
	v_pk_fma_f32 v[14:15], v[144:145], v[204:205], v[14:15] op_sel_hi:[1,0,1]
	v_pk_fma_f32 v[16:17], v[146:147], v[204:205], v[16:17] op_sel_hi:[1,0,1]
	v_pk_fma_f32 v[6:7], v[148:149], v[172:173], v[6:7] op_sel:[0,1,0]
	v_pk_fma_f32 v[8:9], v[150:151], v[172:173], v[8:9] op_sel:[0,1,0]
	v_pk_fma_f32 v[10:11], v[148:149], v[188:189], v[10:11] op_sel:[0,1,0]
	v_pk_fma_f32 v[12:13], v[150:151], v[188:189], v[12:13] op_sel:[0,1,0]
	v_pk_fma_f32 v[14:15], v[148:149], v[204:205], v[14:15] op_sel:[0,1,0]
	v_pk_fma_f32 v[16:17], v[150:151], v[204:205], v[16:17] op_sel:[0,1,0]
	v_pk_fma_f32 v[6:7], v[152:153], v[174:175], v[6:7] op_sel_hi:[1,0,1]
	v_pk_fma_f32 v[8:9], v[154:155], v[174:175], v[8:9] op_sel_hi:[1,0,1]
	v_pk_fma_f32 v[10:11], v[152:153], v[190:191], v[10:11] op_sel_hi:[1,0,1]
	v_pk_fma_f32 v[12:13], v[154:155], v[190:191], v[12:13] op_sel_hi:[1,0,1]
	v_pk_fma_f32 v[14:15], v[152:153], v[206:207], v[14:15] op_sel_hi:[1,0,1]
	v_pk_fma_f32 v[16:17], v[154:155], v[206:207], v[16:17] op_sel_hi:[1,0,1]
	v_pk_fma_f32 v[6:7], v[156:157], v[174:175], v[6:7] op_sel:[0,1,0]
	v_pk_fma_f32 v[8:9], v[158:159], v[174:175], v[8:9] op_sel:[0,1,0]
	v_pk_fma_f32 v[10:11], v[156:157], v[190:191], v[10:11] op_sel:[0,1,0]
	v_pk_fma_f32 v[12:13], v[158:159], v[190:191], v[12:13] op_sel:[0,1,0]
	v_pk_fma_f32 v[14:15], v[156:157], v[206:207], v[14:15] op_sel:[0,1,0]
	v_pk_fma_f32 v[16:17], v[158:159], v[206:207], v[16:17] op_sel:[0,1,0]
	s_add_u32 m0, s94, 0x2400
	s_nop 0
	global_load_lds_dwordx4 v95, s[92:93] nt
	s_add_u32 s92, s92, 0x60000
	s_addc_u32 s93, s93, 0
	s_add_u32 m0, s94, 0x2700
	s_nop 0
	global_load_lds_dwordx4 v95, s[92:93] nt
	s_add_u32 s92, s92, 0x60000
	s_addc_u32 s93, s93, 0
	s_add_u32 m0, s94, 0x2a00
	s_nop 0
	global_load_lds_dwordx4 v95, s[92:93] nt
	s_add_u32 s92, s92, 0x60000
	s_addc_u32 s93, s93, 0
	s_add_u32 m0, s94, 0x2d00
	s_nop 0
	global_load_lds_dwordx4 v95, s[92:93] nt
	s_add_u32 s92, s92, 0x60000
	s_addc_u32 s93, s93, 0
	s_add_i32 s95, s95, -1
	s_cmp_lg_u32 s95, 0
	s_cbranch_scc1 .Lada_loop
	v_mov_b32_e32 v93, s12
	ds_read_b128 v[160:163], v93
	ds_read_b128 v[164:167], v93 offset:16
	ds_read_b128 v[168:171], v93 offset:32
	ds_read_b128 v[172:175], v93 offset:48
	ds_read_b128 v[176:179], v93 offset:8192
	ds_read_b128 v[180:183], v93 offset:8208
	ds_read_b128 v[184:187], v93 offset:8224
	ds_read_b128 v[188:191], v93 offset:8240
	ds_read_b128 v[192:195], v93 offset:16384
	ds_read_b128 v[196:199], v93 offset:16400
	ds_read_b128 v[200:203], v93 offset:16416
	ds_read_b128 v[204:207], v93 offset:16432
	s_add_i32 s12, s12, 64
	s_waitcnt vmcnt(12)
	ds_read_b128 v[96:99], v94
	ds_read_b128 v[100:103], v94 offset:768
	ds_read_b128 v[104:107], v94 offset:1536
	ds_read_b128 v[108:111], v94 offset:2304
	s_waitcnt lgkmcnt(0)
	v_pk_fma_f32 v[6:7], v[96:97], v[160:161], v[6:7] op_sel_hi:[1,0,1]
	v_pk_fma_f32 v[8:9], v[98:99], v[160:161], v[8:9] op_sel_hi:[1,0,1]
	v_pk_fma_f32 v[10:11], v[96:97], v[176:177], v[10:11] op_sel_hi:[1,0,1]
	v_pk_fma_f32 v[12:13], v[98:99], v[176:177], v[12:13] op_sel_hi:[1,0,1]
	v_pk_fma_f32 v[14:15], v[96:97], v[192:193], v[14:15] op_sel_hi:[1,0,1]
	v_pk_fma_f32 v[16:17], v[98:99], v[192:193], v[16:17] op_sel_hi:[1,0,1]
	v_pk_fma_f32 v[6:7], v[100:101], v[160:161], v[6:7] op_sel:[0,1,0]
	v_pk_fma_f32 v[8:9], v[102:103], v[160:161], v[8:9] op_sel:[0,1,0]
	v_pk_fma_f32 v[10:11], v[100:101], v[176:177], v[10:11] op_sel:[0,1,0]
	v_pk_fma_f32 v[12:13], v[102:103], v[176:177], v[12:13] op_sel:[0,1,0]
	v_pk_fma_f32 v[14:15], v[100:101], v[192:193], v[14:15] op_sel:[0,1,0]
	v_pk_fma_f32 v[16:17], v[102:103], v[192:193], v[16:17] op_sel:[0,1,0]
	v_pk_fma_f32 v[6:7], v[104:105], v[162:163], v[6:7] op_sel_hi:[1,0,1]
	v_pk_fma_f32 v[8:9], v[106:107], v[162:163], v[8:9] op_sel_hi:[1,0,1]
	v_pk_fma_f32 v[10:11], v[104:105], v[178:179], v[10:11] op_sel_hi:[1,0,1]
	v_pk_fma_f32 v[12:13], v[106:107], v[178:179], v[12:13] op_sel_hi:[1,0,1]
	v_pk_fma_f32 v[14:15], v[104:105], v[194:195], v[14:15] op_sel_hi:[1,0,1]
	v_pk_fma_f32 v[16:17], v[106:107], v[194:195], v[16:17] op_sel_hi:[1,0,1]
	v_pk_fma_f32 v[6:7], v[108:109], v[162:163], v[6:7] op_sel:[0,1,0]
	v_pk_fma_f32 v[8:9], v[110:111], v[162:163], v[8:9] op_sel:[0,1,0]
	v_pk_fma_f32 v[10:11], v[108:109], v[178:179], v[10:11] op_sel:[0,1,0]
	v_pk_fma_f32 v[12:13], v[110:111], v[178:179], v[12:13] op_sel:[0,1,0]
	v_pk_fma_f32 v[14:15], v[108:109], v[194:195], v[14:15] op_sel:[0,1,0]
	v_pk_fma_f32 v[16:17], v[110:111], v[194:195], v[16:17] op_sel:[0,1,0]
	s_waitcnt vmcnt(8)
	ds_read_b128 v[112:115], v94 offset:3072
	ds_read_b128 v[116:119], v94 offset:3840
	ds_read_b128 v[120:123], v94 offset:4608
	ds_read_b128 v[124:127], v94 offset:5376
	s_waitcnt lgkmcnt(0)
; #define GAS __attribute__((address_space(1)))
; #define LAS __attribute__((address_space(3)))
; DI void phase_prologue(const Frame& F0, const Args& a) {
;     ...
;             if (F.lane < 48) {
;                 const int kb = F.wave * 256;
; #pragma unroll 16
;                 for (int k = 0; k < 256; ++k) {
;                     const f32x4 w = __builtin_nontemporal_load((const GAS f32x4*)(W + (size_t)(kb + k) * NADA + F.lane * 4));
;                     const float s0 = sv[kb + k], s1 = sv[DM + kb + k], s2 = sv[2 * DM + kb + k];
;                     acc0 += w * s0; acc1 += w * s1; acc2 += w * s2;
;                 }
;                 *(LAS f32x4*)(red + (F.wave * 3 + 0) * 192 + F.lane * 4) = acc0;
;                 *(LAS f32x4*)(red + (F.wave * 3 + 1) * 192 + F.lane * 4) = acc1;
;                 *(LAS f32x4*)(red + (F.wave * 3 + 2) * 192 + F.lane * 4) = acc2;
	v_pk_fma_f32 v[6:7], v[112:113], v[164:165], v[6:7] op_sel_hi:[1,0,1]
	v_pk_fma_f32 v[8:9], v[114:115], v[164:165], v[8:9] op_sel_hi:[1,0,1]
	v_pk_fma_f32 v[10:11], v[112:113], v[180:181], v[10:11] op_sel_hi:[1,0,1]
	v_pk_fma_f32 v[12:13], v[114:115], v[180:181], v[12:13] op_sel_hi:[1,0,1]
	v_pk_fma_f32 v[14:15], v[112:113], v[196:197], v[14:15] op_sel_hi:[1,0,1]
	v_pk_fma_f32 v[16:17], v[114:115], v[196:197], v[16:17] op_sel_hi:[1,0,1]
	v_pk_fma_f32 v[6:7], v[116:117], v[164:165], v[6:7] op_sel:[0,1,0]
	v_pk_fma_f32 v[8:9], v[118:119], v[164:165], v[8:9] op_sel:[0,1,0]
	v_pk_fma_f32 v[10:11], v[116:117], v[180:181], v[10:11] op_sel:[0,1,0]
	v_pk_fma_f32 v[12:13], v[118:119], v[180:181], v[12:13] op_sel:[0,1,0]
	v_pk_fma_f32 v[14:15], v[116:117], v[196:197], v[14:15] op_sel:[0,1,0]
	v_pk_fma_f32 v[16:17], v[118:119], v[196:197], v[16:17] op_sel:[0,1,0]
	v_pk_fma_f32 v[6:7], v[120:121], v[166:167], v[6:7] op_sel_hi:[1,0,1]
	v_pk_fma_f32 v[8:9], v[122:123], v[166:167], v[8:9] op_sel_hi:[1,0,1]
	v_pk_fma_f32 v[10:11], v[120:121], v[182:183], v[10:11] op_sel_hi:[1,0,1]
	v_pk_fma_f32 v[12:13], v[122:123], v[182:183], v[12:13] op_sel_hi:[1,0,1]
	v_pk_fma_f32 v[14:15], v[120:121], v[198:199], v[14:15] op_sel_hi:[1,0,1]
	v_pk_fma_f32 v[16:17], v[122:123], v[198:199], v[16:17] op_sel_hi:[1,0,1]
	v_pk_fma_f32 v[6:7], v[124:125], v[166:167], v[6:7] op_sel:[0,1,0]
	v_pk_fma_f32 v[8:9], v[126:127], v[166:167], v[8:9] op_sel:[0,1,0]
	v_pk_fma_f32 v[10:11], v[124:125], v[182:183], v[10:11] op_sel:[0,1,0]
	v_pk_fma_f32 v[12:13], v[126:127], v[182:183], v[12:13] op_sel:[0,1,0]
	v_pk_fma_f32 v[14:15], v[124:125], v[198:199], v[14:15] op_sel:[0,1,0]
	v_pk_fma_f32 v[16:17], v[126:127], v[198:199], v[16:17] op_sel:[0,1,0]
	s_waitcnt vmcnt(4)
	ds_read_b128 v[128:131], v94 offset:6144
	ds_read_b128 v[132:135], v94 offset:6912
	ds_read_b128 v[136:139], v94 offset:7680
	ds_read_b128 v[140:143], v94 offset:8448
	s_waitcnt lgkmcnt(0)
	v_pk_fma_f32 v[6:7], v[128:129], v[168:169], v[6:7] op_sel_hi:[1,0,1]
	v_pk_fma_f32 v[8:9], v[130:131], v[168:169], v[8:9] op_sel_hi:[1,0,1]
	v_pk_fma_f32 v[10:11], v[128:129], v[184:185], v[10:11] op_sel_hi:[1,0,1]
	v_pk_fma_f32 v[12:13], v[130:131], v[184:185], v[12:13] op_sel_hi:[1,0,1]
	v_pk_fma_f32 v[14:15], v[128:129], v[200:201], v[14:15] op_sel_hi:[1,0,1]
	v_pk_fma_f32 v[16:17], v[130:131], v[200:201], v[16:17] op_sel_hi:[1,0,1]
	v_pk_fma_f32 v[6:7], v[132:133], v[168:169], v[6:7] op_sel:[0,1,0]
	v_pk_fma_f32 v[8:9], v[134:135], v[168:169], v[8:9] op_sel:[0,1,0]
	v_pk_fma_f32 v[10:11], v[132:133], v[184:185], v[10:11] op_sel:[0,1,0]
	v_pk_fma_f32 v[12:13], v[134:135], v[184:185], v[12:13] op_sel:[0,1,0]
	v_pk_fma_f32 v[14:15], v[132:133], v[200:201], v[14:15] op_sel:[0,1,0]
	v_pk_fma_f32 v[16:17], v[134:135], v[200:201], v[16:17] op_sel:[0,1,0]
	v_pk_fma_f32 v[6:7], v[136:137], v[170:171], v[6:7] op_sel_hi:[1,0,1]
	v_pk_fma_f32 v[8:9], v[138:139], v[170:171], v[8:9] op_sel_hi:[1,0,1]
	v_pk_fma_f32 v[10:11], v[136:137], v[186:187], v[10:11] op_sel_hi:[1,0,1]
	v_pk_fma_f32 v[12:13], v[138:139], v[186:187], v[12:13] op_sel_hi:[1,0,1]
	v_pk_fma_f32 v[14:15], v[136:137], v[202:203], v[14:15] op_sel_hi:[1,0,1]
	v_pk_fma_f32 v[16:17], v[138:139], v[202:203], v[16:17] op_sel_hi:[1,0,1]
	v_pk_fma_f32 v[6:7], v[140:141], v[170:171], v[6:7] op_sel:[0,1,0]
	v_pk_fma_f32 v[8:9], v[142:143], v[170:171], v[8:9] op_sel:[0,1,0]
	v_pk_fma_f32 v[10:11], v[140:141], v[186:187], v[10:11] op_sel:[0,1,0]
	v_pk_fma_f32 v[12:13], v[142:143], v[186:187], v[12:13] op_sel:[0,1,0]
	v_pk_fma_f32 v[14:15], v[140:141], v[202:203], v[14:15] op_sel:[0,1,0]
	v_pk_fma_f32 v[16:17], v[142:143], v[202:203], v[16:17] op_sel:[0,1,0]
	s_waitcnt vmcnt(0)
	ds_read_b128 v[144:147], v94 offset:9216
	ds_read_b128 v[148:151], v94 offset:9984
	ds_read_b128 v[152:155], v94 offset:10752
	ds_read_b128 v[156:159], v94 offset:11520
	s_waitcnt lgkmcnt(0)
	v_pk_fma_f32 v[6:7], v[144:145], v[172:173], v[6:7] op_sel_hi:[1,0,1]
	v_pk_fma_f32 v[8:9], v[146:147], v[172:173], v[8:9] op_sel_hi:[1,0,1]
	v_pk_fma_f32 v[10:11], v[144:145], v[188:189], v[10:11] op_sel_hi:[1,0,1]
	v_pk_fma_f32 v[12:13], v[146:147], v[188:189], v[12:13] op_sel_hi:[1,0,1]
	v_pk_fma_f32 v[14:15], v[144:145], v[204:205], v[14:15] op_sel_hi:[1,0,1]
	v_pk_fma_f32 v[16:17], v[146:147], v[204:205], v[16:17] op_sel_hi:[1,0,1]
	v_pk_fma_f32 v[6:7], v[148:149], v[172:173], v[6:7] op_sel:[0,1,0]
	v_pk_fma_f32 v[8:9], v[150:151], v[172:173], v[8:9] op_sel:[0,1,0]
	v_pk_fma_f32 v[10:11], v[148:149], v[188:189], v[10:11] op_sel:[0,1,0]
	v_pk_fma_f32 v[12:13], v[150:151], v[188:189], v[12:13] op_sel:[0,1,0]
	v_pk_fma_f32 v[14:15], v[148:149], v[204:205], v[14:15] op_sel:[0,1,0]
	v_pk_fma_f32 v[16:17], v[150:151], v[204:205], v[16:17] op_sel:[0,1,0]
	v_pk_fma_f32 v[6:7], v[152:153], v[174:175], v[6:7] op_sel_hi:[1,0,1]
	v_pk_fma_f32 v[8:9], v[154:155], v[174:175], v[8:9] op_sel_hi:[1,0,1]
	v_pk_fma_f32 v[10:11], v[152:153], v[190:191], v[10:11] op_sel_hi:[1,0,1]
	v_pk_fma_f32 v[12:13], v[154:155], v[190:191], v[12:13] op_sel_hi:[1,0,1]
	v_pk_fma_f32 v[14:15], v[152:153], v[206:207], v[14:15] op_sel_hi:[1,0,1]
	v_pk_fma_f32 v[16:17], v[154:155], v[206:207], v[16:17] op_sel_hi:[1,0,1]
	v_pk_fma_f32 v[6:7], v[156:157], v[174:175], v[6:7] op_sel:[0,1,0]
	v_pk_fma_f32 v[8:9], v[158:159], v[174:175], v[8:9] op_sel:[0,1,0]
	v_pk_fma_f32 v[10:11], v[156:157], v[190:191], v[10:11] op_sel:[0,1,0]
	v_pk_fma_f32 v[12:13], v[158:159], v[190:191], v[12:13] op_sel:[0,1,0]
	v_pk_fma_f32 v[14:15], v[156:157], v[206:207], v[14:15] op_sel:[0,1,0]
	v_pk_fma_f32 v[16:17], v[158:159], v[206:207], v[16:17] op_sel:[0,1,0]
	ds_write_b128 v79, v[6:9] offset:24576
	ds_write_b128 v79, v[10:13] offset:25344
	ds_write_b128 v79, v[14:17] offset:26112
